# combined: kscale/w_in item loads batched, chunk-state loads pipelined, KV-epilogue rstd loads hoisted
# speedup vs baseline: 1.0111x; 1.0111x over previous
.Lin_tail:
	s_waitcnt lgkmcnt(0)
	ds_read2_b32 v[14:15], v76 offset0:33 offset1:41
	ds_read2_b32 v[88:89], v76 offset1:8
	ds_read2_b32 v[90:91], v76 offset0:66 offset1:74
	ds_read2_b32 v[92:93], v76 offset0:99 offset1:107
	ds_read2_b32 v[94:95], v76 offset0:132 offset1:140
	ds_read2_b32 v[96:97], v76 offset0:165 offset1:173
	ds_read2_b32 v[98:99], v76 offset0:198 offset1:206
	ds_read2_b32 v[100:101], v76 offset0:231 offset1:239
	v_add_u32_e32 v0, s4, v75
	v_add_u32_e32 v104, 0x25200, v0
	s_ashr_i32 s1, s0, 31
	v_ashrrev_i32_e32 v105, 31, v104
	v_lshl_add_u64 v[102:103], s[0:1], 1, v[12:13]
	v_lshlrev_b64 v[104:105], 11, v[104:105]
	s_waitcnt lgkmcnt(6)
	v_cvt_pk_bf16_f32 v84, v88, v14
	s_waitcnt lgkmcnt(4)
	v_cvt_pk_bf16_f32 v85, v90, v92
	s_waitcnt lgkmcnt(2)
	v_cvt_pk_bf16_f32 v86, v94, v96
	s_waitcnt lgkmcnt(0)
	v_cvt_pk_bf16_f32 v87, v98, v100
	v_lshl_add_u64 v[104:105], v[102:103], 0, v[104:105]
	v_add_u32_e32 v14, 0x25208, v0
	global_store_dwordx4 v[104:105], v[84:87], off
	s_nop 1
	v_cvt_pk_bf16_f32 v84, v89, v15
	v_ashrrev_i32_e32 v15, 31, v14
	v_cvt_pk_bf16_f32 v85, v91, v93
	v_cvt_pk_bf16_f32 v86, v95, v97
	v_cvt_pk_bf16_f32 v87, v99, v101
	v_lshlrev_b64 v[14:15], 11, v[14:15]
	ds_read2_b32 v[88:89], v76 offset0:49 offset1:57
	ds_read2_b32 v[90:91], v76 offset0:16 offset1:24
	ds_read2_b32 v[92:93], v76 offset0:82 offset1:90
	ds_read2_b32 v[94:95], v76 offset0:115 offset1:123
	ds_read2_b32 v[96:97], v76 offset0:148 offset1:156
	ds_read2_b32 v[98:99], v76 offset0:181 offset1:189
	ds_read2_b32 v[100:101], v76 offset0:214 offset1:222
	ds_read2_b32 v[104:105], v76 offset0:247 offset1:255
	v_lshl_add_u64 v[14:15], v[102:103], 0, v[14:15]
	global_store_dwordx4 v[14:15], v[84:87], off
	v_add_u32_e32 v14, 0x25210, v0
	v_ashrrev_i32_e32 v15, 31, v14
	v_lshlrev_b64 v[14:15], 11, v[14:15]
	s_waitcnt lgkmcnt(6)
	v_cvt_pk_bf16_f32 v84, v90, v88
	s_waitcnt lgkmcnt(4)
	v_cvt_pk_bf16_f32 v85, v92, v94
	s_waitcnt lgkmcnt(2)
	v_cvt_pk_bf16_f32 v86, v96, v98
	s_waitcnt lgkmcnt(0)
	v_cvt_pk_bf16_f32 v87, v100, v104
	v_lshl_add_u64 v[14:15], v[102:103], 0, v[14:15]
	global_store_dwordx4 v[14:15], v[84:87], off
	v_add_u32_e32 v14, 0x25218, v0
	v_ashrrev_i32_e32 v15, 31, v14
	v_lshlrev_b64 v[14:15], 11, v[14:15]
	v_cvt_pk_bf16_f32 v84, v91, v89
	v_cvt_pk_bf16_f32 v85, v93, v95
	v_cvt_pk_bf16_f32 v86, v97, v99
	v_cvt_pk_bf16_f32 v87, v101, v105
	v_lshl_add_u64 v[14:15], v[102:103], 0, v[14:15]
	global_store_dwordx4 v[14:15], v[84:87], off
	s_waitcnt lgkmcnt(0)

.LBB0_55:
	s_andn2_b64 vcc, exec, s[0:1]
	s_cbranch_vccnz .LBB0_122
	s_add_i32 s0, s18, 0x1b00
	s_and_b32 s4, s0, 0x1c0
	s_add_i32 s0, s16, 0x1b000
	s_and_b32 s10, s0, 0x3e0
	v_or_b32_e32 v0, s10, v16
	v_readlane_b32 s36, v254, 31
	v_lshlrev_b32_e32 v0, 2, v0
	v_readlane_b32 s40, v254, 35
	v_readlane_b32 s41, v254, 36
	v_or_b32_e32 v85, s4, v17
	v_readlane_b32 s38, v254, 33
	v_lshl_add_u64 v[14:15], s[40:41], 0, v[0:1]
	s_movk_i32 s36, 0x1000
	s_and_b64 vcc, exec, s[6:7]
	s_cbranch_vccz .Lkv_slow
	v_readlane_b32 s38, v254, 33
	v_readlane_b32 s39, v254, 34
	v_add_lshl_u32 v85, s4, v17, 2
	v_or_b32_e32 v86, s4, v17
	v_mad_u64_u32 v[88:89], s[30:31], v86, s36, v[14:15]
	global_load_dword v144, v[88:89], off nt
	v_or_b32_e32 v86, s4, v20
	v_mad_u64_u32 v[88:89], s[30:31], v86, s36, v[14:15]
	global_load_dword v145, v[88:89], off nt
	v_or_b32_e32 v86, s4, v22
	v_mad_u64_u32 v[88:89], s[30:31], v86, s36, v[14:15]
	global_load_dword v146, v[88:89], off nt
	v_or_b32_e32 v86, s4, v24
	v_mad_u64_u32 v[88:89], s[30:31], v86, s36, v[14:15]
	global_load_dword v147, v[88:89], off nt
	v_or_b32_e32 v86, s4, v26
	v_mad_u64_u32 v[88:89], s[30:31], v86, s36, v[14:15]
	global_load_dword v148, v[88:89], off nt
	v_or_b32_e32 v86, s4, v28
	v_mad_u64_u32 v[88:89], s[30:31], v86, s36, v[14:15]
	global_load_dword v149, v[88:89], off nt
	v_or_b32_e32 v86, s4, v30
	v_mad_u64_u32 v[88:89], s[30:31], v86, s36, v[14:15]
	global_load_dword v150, v[88:89], off nt
	v_or_b32_e32 v86, s4, v32
	v_mad_u64_u32 v[88:89], s[30:31], v86, s36, v[14:15]
	global_load_dword v151, v[88:89], off nt
	v_or_b32_e32 v86, s4, v34
	v_mad_u64_u32 v[88:89], s[30:31], v86, s36, v[14:15]
	global_load_dword v152, v[88:89], off nt
	v_or_b32_e32 v86, s4, v36
	v_mad_u64_u32 v[88:89], s[30:31], v86, s36, v[14:15]
	global_load_dword v153, v[88:89], off nt
	v_or_b32_e32 v86, s4, v38
	v_mad_u64_u32 v[88:89], s[30:31], v86, s36, v[14:15]
	global_load_dword v154, v[88:89], off nt
	v_or_b32_e32 v86, s4, v40
	v_mad_u64_u32 v[88:89], s[30:31], v86, s36, v[14:15]
	global_load_dword v155, v[88:89], off nt
	v_or_b32_e32 v86, s4, v42
	v_mad_u64_u32 v[88:89], s[30:31], v86, s36, v[14:15]
	global_load_dword v156, v[88:89], off nt
	v_or_b32_e32 v86, s4, v44
	v_mad_u64_u32 v[88:89], s[30:31], v86, s36, v[14:15]
	global_load_dword v157, v[88:89], off nt
	v_or_b32_e32 v86, s4, v46
	v_mad_u64_u32 v[88:89], s[30:31], v86, s36, v[14:15]
	global_load_dword v158, v[88:89], off nt
	v_or_b32_e32 v86, s4, v48
	v_mad_u64_u32 v[88:89], s[30:31], v86, s36, v[14:15]
	global_load_dword v159, v[88:89], off nt
	v_or_b32_e32 v86, s4, v50
	v_mad_u64_u32 v[88:89], s[30:31], v86, s36, v[14:15]
	global_load_dword v160, v[88:89], off nt
	v_or_b32_e32 v86, s4, v52
	v_mad_u64_u32 v[88:89], s[30:31], v86, s36, v[14:15]
	global_load_dword v161, v[88:89], off nt
	v_or_b32_e32 v86, s4, v54
	v_mad_u64_u32 v[88:89], s[30:31], v86, s36, v[14:15]
	global_load_dword v162, v[88:89], off nt
	v_or_b32_e32 v86, s4, v56
	v_mad_u64_u32 v[88:89], s[30:31], v86, s36, v[14:15]
	global_load_dword v163, v[88:89], off nt
	v_or_b32_e32 v86, s4, v58
	v_mad_u64_u32 v[88:89], s[30:31], v86, s36, v[14:15]
	global_load_dword v164, v[88:89], off nt
	v_or_b32_e32 v86, s4, v60
	v_mad_u64_u32 v[88:89], s[30:31], v86, s36, v[14:15]
	global_load_dword v165, v[88:89], off nt
	v_or_b32_e32 v86, s4, v62
	v_mad_u64_u32 v[88:89], s[30:31], v86, s36, v[14:15]
	global_load_dword v166, v[88:89], off nt
	v_or_b32_e32 v86, s4, v64
	v_mad_u64_u32 v[88:89], s[30:31], v86, s36, v[14:15]
	global_load_dword v167, v[88:89], off nt
	v_or_b32_e32 v86, s4, v66
	v_mad_u64_u32 v[88:89], s[30:31], v86, s36, v[14:15]
	global_load_dword v168, v[88:89], off nt
	v_or_b32_e32 v86, s4, v68
	v_mad_u64_u32 v[88:89], s[30:31], v86, s36, v[14:15]
	global_load_dword v169, v[88:89], off nt
	v_or_b32_e32 v86, s4, v69
	v_mad_u64_u32 v[88:89], s[30:31], v86, s36, v[14:15]
	global_load_dword v170, v[88:89], off nt
	v_or_b32_e32 v86, s4, v70
	v_mad_u64_u32 v[88:89], s[30:31], v86, s36, v[14:15]
	global_load_dword v171, v[88:89], off nt
	v_or_b32_e32 v86, s4, v71
	v_mad_u64_u32 v[88:89], s[30:31], v86, s36, v[14:15]
	global_load_dword v172, v[88:89], off nt
	v_or_b32_e32 v86, s4, v72
	v_mad_u64_u32 v[88:89], s[30:31], v86, s36, v[14:15]
	global_load_dword v173, v[88:89], off nt
	v_or_b32_e32 v86, s4, v73
	v_mad_u64_u32 v[88:89], s[30:31], v86, s36, v[14:15]
	global_load_dword v174, v[88:89], off nt
	v_or_b32_e32 v86, s4, v74
	v_mad_u64_u32 v[88:89], s[30:31], v86, s36, v[14:15]
	global_load_dword v175, v[88:89], off nt
	global_load_dword v176, v85, s[38:39]
	global_load_dword v177, v85, s[38:39] offset:8
	global_load_dword v178, v85, s[38:39] offset:16
	global_load_dword v179, v85, s[38:39] offset:24
	global_load_dword v180, v85, s[38:39] offset:32
	global_load_dword v181, v85, s[38:39] offset:40
	global_load_dword v182, v85, s[38:39] offset:48
	global_load_dword v183, v85, s[38:39] offset:56
	global_load_dword v184, v85, s[38:39] offset:64
	global_load_dword v185, v85, s[38:39] offset:72
	global_load_dword v186, v85, s[38:39] offset:80
	global_load_dword v187, v85, s[38:39] offset:88
	global_load_dword v188, v85, s[38:39] offset:96
	global_load_dword v189, v85, s[38:39] offset:104
	global_load_dword v190, v85, s[38:39] offset:112
	global_load_dword v191, v85, s[38:39] offset:120
	global_load_dword v192, v85, s[38:39] offset:128
	global_load_dword v193, v85, s[38:39] offset:136
	global_load_dword v194, v85, s[38:39] offset:144
	global_load_dword v195, v85, s[38:39] offset:152
	global_load_dword v196, v85, s[38:39] offset:160
	global_load_dword v197, v85, s[38:39] offset:168
	global_load_dword v198, v85, s[38:39] offset:176
	global_load_dword v199, v85, s[38:39] offset:184
	global_load_dword v200, v85, s[38:39] offset:192
	global_load_dword v201, v85, s[38:39] offset:200
	global_load_dword v202, v85, s[38:39] offset:208
	global_load_dword v203, v85, s[38:39] offset:216
	global_load_dword v204, v85, s[38:39] offset:224
	global_load_dword v205, v85, s[38:39] offset:232
	global_load_dword v206, v85, s[38:39] offset:240
	global_load_dword v207, v85, s[38:39] offset:248
	s_waitcnt vmcnt(0)
	v_add_u32_e32 v86, v18, v19
	v_mul_f32_e32 v144, v144, v176
	v_mul_f32_e32 v145, v145, v177
	v_mul_f32_e32 v146, v146, v178
	v_mul_f32_e32 v147, v147, v179
	v_mul_f32_e32 v148, v148, v180
	v_mul_f32_e32 v149, v149, v181
	v_mul_f32_e32 v150, v150, v182
	v_mul_f32_e32 v151, v151, v183
	v_mul_f32_e32 v152, v152, v184
	v_mul_f32_e32 v153, v153, v185
	v_mul_f32_e32 v154, v154, v186
	v_mul_f32_e32 v155, v155, v187
	v_mul_f32_e32 v156, v156, v188
	v_mul_f32_e32 v157, v157, v189
	v_mul_f32_e32 v158, v158, v190
	v_mul_f32_e32 v159, v159, v191
	v_mul_f32_e32 v160, v160, v192
	v_mul_f32_e32 v161, v161, v193
	v_mul_f32_e32 v162, v162, v194
	v_mul_f32_e32 v163, v163, v195
	v_mul_f32_e32 v164, v164, v196
	v_mul_f32_e32 v165, v165, v197
	v_mul_f32_e32 v166, v166, v198
	v_mul_f32_e32 v167, v167, v199
	v_mul_f32_e32 v168, v168, v200
	v_mul_f32_e32 v169, v169, v201
	v_mul_f32_e32 v170, v170, v202
	v_mul_f32_e32 v171, v171, v203
	v_mul_f32_e32 v172, v172, v204
	v_mul_f32_e32 v173, v173, v205
	v_mul_f32_e32 v174, v174, v206
	v_mul_f32_e32 v175, v175, v207
	ds_write_b32 v86, v144
	ds_write_b32 v86, v145 offset:264
	ds_write_b32 v86, v146 offset:528
	ds_write_b32 v86, v147 offset:792
	ds_write_b32 v86, v148 offset:1056
	ds_write_b32 v86, v149 offset:1320
	ds_write_b32 v86, v150 offset:1584
	ds_write_b32 v86, v151 offset:1848
	ds_write_b32 v86, v152 offset:2112
	ds_write_b32 v86, v153 offset:2376
	ds_write_b32 v86, v154 offset:2640
	ds_write_b32 v86, v155 offset:2904
	ds_write_b32 v86, v156 offset:3168
	ds_write_b32 v86, v157 offset:3432
	ds_write_b32 v86, v158 offset:3696
	ds_write_b32 v86, v159 offset:3960
	ds_write_b32 v86, v160 offset:4224
	ds_write_b32 v86, v161 offset:4488
	ds_write_b32 v86, v162 offset:4752
	ds_write_b32 v86, v163 offset:5016
	ds_write_b32 v86, v164 offset:5280
	ds_write_b32 v86, v165 offset:5544
	ds_write_b32 v86, v166 offset:5808
	ds_write_b32 v86, v167 offset:6072
	ds_write_b32 v86, v168 offset:6336
	ds_write_b32 v86, v169 offset:6600
	ds_write_b32 v86, v170 offset:6864
	ds_write_b32 v86, v171 offset:7128
	ds_write_b32 v86, v172 offset:7392
	ds_write_b32 v86, v173 offset:7656
	ds_write_b32 v86, v174 offset:7920
	ds_write_b32 v86, v175 offset:8184
	s_branch .Lkv_tail
.Lkv_slow:
	v_lshlrev_b32_e32 v0, 12, v85
	v_lshl_add_u64 v[86:87], v[14:15], 0, v[0:1]
	global_load_dword v84, v[86:87], off nt
	v_cndmask_b32_e64 v0, 0, 1, s[6:7]
	v_readlane_b32 s39, v254, 34
	v_cmp_ne_u32_e64 s[0:1], 1, v0
	s_andn2_b64 vcc, exec, s[6:7]
	v_readlane_b32 s37, v254, 32
	v_readlane_b32 s42, v254, 37
	v_readlane_b32 s43, v254, 38
	v_readlane_b32 s44, v254, 39
	v_readlane_b32 s45, v254, 40
	v_readlane_b32 s46, v254, 41
	v_readlane_b32 s47, v254, 42
	v_readlane_b32 s48, v254, 43
	v_readlane_b32 s49, v254, 44
	v_readlane_b32 s50, v254, 45
	v_readlane_b32 s51, v254, 46
	s_cbranch_vccnz .LBB0_58
	v_lshlrev_b32_e32 v0, 2, v85
	global_load_dword v0, v0, s[38:39]
	s_waitcnt vmcnt(0)
	v_mul_f32_e32 v84, v84, v0

.Lkv_tail:
	s_waitcnt lgkmcnt(0)
	ds_read2_b32 v[14:15], v76 offset0:33 offset1:41
	ds_read2_b32 v[88:89], v76 offset1:8
	ds_read2_b32 v[90:91], v76 offset0:66 offset1:74
	ds_read2_b32 v[92:93], v76 offset0:99 offset1:107
	ds_read2_b32 v[94:95], v76 offset0:132 offset1:140
	ds_read2_b32 v[96:97], v76 offset0:165 offset1:173
	ds_read2_b32 v[98:99], v76 offset0:198 offset1:206
	ds_read2_b32 v[100:101], v76 offset0:231 offset1:239
	s_lshl_b32 s4, s4, 1
	s_waitcnt vmcnt(0)
	v_or_b32_e32 v0, s10, v75
	v_lshl_add_u64 v[102:103], v[8:9], 0, s[4:5]
	v_lshlrev_b32_e32 v0, 9, v0
	s_waitcnt lgkmcnt(6)
	v_cvt_pk_bf16_f32 v84, v88, v14
	s_waitcnt lgkmcnt(4)
	v_cvt_pk_bf16_f32 v85, v90, v92
	s_waitcnt lgkmcnt(2)
	v_cvt_pk_bf16_f32 v86, v94, v96
	s_waitcnt lgkmcnt(0)
	v_cvt_pk_bf16_f32 v87, v98, v100
	v_lshl_add_u64 v[104:105], v[102:103], 0, v[0:1]
	global_store_dwordx4 v[104:105], v[84:87], off
	v_or_b32_e32 v0, s10, v77
	v_lshlrev_b32_e32 v0, 9, v0
	v_cvt_pk_bf16_f32 v84, v89, v15
	v_cvt_pk_bf16_f32 v85, v91, v93
	v_cvt_pk_bf16_f32 v86, v95, v97
	v_cvt_pk_bf16_f32 v87, v99, v101
	ds_read2_b32 v[88:89], v76 offset0:49 offset1:57
	ds_read2_b32 v[90:91], v76 offset0:16 offset1:24
	ds_read2_b32 v[92:93], v76 offset0:82 offset1:90
	ds_read2_b32 v[94:95], v76 offset0:115 offset1:123
	ds_read2_b32 v[96:97], v76 offset0:148 offset1:156
	ds_read2_b32 v[98:99], v76 offset0:181 offset1:189
	ds_read2_b32 v[100:101], v76 offset0:214 offset1:222
	ds_read2_b32 v[104:105], v76 offset0:247 offset1:255
	v_lshl_add_u64 v[14:15], v[102:103], 0, v[0:1]
	v_or_b32_e32 v0, s10, v78
	v_lshlrev_b32_e32 v0, 9, v0
	global_store_dwordx4 v[14:15], v[84:87], off
	v_lshl_add_u64 v[14:15], v[102:103], 0, v[0:1]
	v_or_b32_e32 v0, s10, v79
	s_waitcnt lgkmcnt(6)
	v_cvt_pk_bf16_f32 v84, v90, v88
	s_waitcnt lgkmcnt(4)
	v_cvt_pk_bf16_f32 v85, v92, v94
	s_waitcnt lgkmcnt(2)
	v_cvt_pk_bf16_f32 v86, v96, v98
	s_waitcnt lgkmcnt(0)
	v_cvt_pk_bf16_f32 v87, v100, v104
	v_lshlrev_b32_e32 v0, 9, v0
	global_store_dwordx4 v[14:15], v[84:87], off
	v_lshl_add_u64 v[14:15], v[102:103], 0, v[0:1]
	s_nop 0
	v_cvt_pk_bf16_f32 v84, v91, v89
	v_cvt_pk_bf16_f32 v85, v93, v95
	v_cvt_pk_bf16_f32 v86, v97, v99
	v_cvt_pk_bf16_f32 v87, v101, v105
	global_store_dwordx4 v[14:15], v[84:87], off
	s_waitcnt lgkmcnt(0)

.LBB0_123:
	s_andn2_b64 vcc, exec, s[0:1]
	s_cbranch_vccnz .LBB0_190
	s_xor_b32 s0, s29, 0xff80
	s_and_b32 s1, s0, 0xff
	s_mulk_i32 s1, 0xab
	s_bfe_u32 s1, s1, 0x4000c
	s_mul_i32 s4, s1, 24
	s_sub_i32 s0, s0, s4
	s_and_b32 s0, s0, 0xff
	s_lshl_b32 s10, s0, 5
	v_or_b32_e32 v0, s10, v16
	v_readlane_b32 s36, v254, 31
	s_lshl_b32 s4, s1, 6
	v_lshlrev_b32_e32 v0, 2, v0
	v_readlane_b32 s37, v254, 32
	v_or_b32_e32 v84, s4, v17
	v_cndmask_b32_e64 v85, 0, 1, s[8:9]
	v_lshl_add_u64 v[14:15], s[36:37], 0, v[0:1]
	s_and_b64 vcc, exec, s[8:9]
	s_cbranch_vccz .Lq_slow
	v_readlane_b32 s50, v254, 17
	v_readlane_b32 s51, v254, 18
	v_add_lshl_u32 v85, s4, v17, 2
	v_or_b32_e32 v86, s4, v17
	v_mad_u64_u32 v[88:89], s[30:31], v86, s24, v[14:15]
	global_load_dword v144, v[88:89], off nt
	v_or_b32_e32 v86, s4, v20
	v_mad_u64_u32 v[88:89], s[30:31], v86, s24, v[14:15]
	global_load_dword v145, v[88:89], off nt
	v_or_b32_e32 v86, s4, v22
	v_mad_u64_u32 v[88:89], s[30:31], v86, s24, v[14:15]
	global_load_dword v146, v[88:89], off nt
	v_or_b32_e32 v86, s4, v24
	v_mad_u64_u32 v[88:89], s[30:31], v86, s24, v[14:15]
	global_load_dword v147, v[88:89], off nt
	v_or_b32_e32 v86, s4, v26
	v_mad_u64_u32 v[88:89], s[30:31], v86, s24, v[14:15]
	global_load_dword v148, v[88:89], off nt
	v_or_b32_e32 v86, s4, v28
	v_mad_u64_u32 v[88:89], s[30:31], v86, s24, v[14:15]
	global_load_dword v149, v[88:89], off nt
	v_or_b32_e32 v86, s4, v30
	v_mad_u64_u32 v[88:89], s[30:31], v86, s24, v[14:15]
	global_load_dword v150, v[88:89], off nt
	v_or_b32_e32 v86, s4, v32
	v_mad_u64_u32 v[88:89], s[30:31], v86, s24, v[14:15]
	global_load_dword v151, v[88:89], off nt
	v_or_b32_e32 v86, s4, v34
	v_mad_u64_u32 v[88:89], s[30:31], v86, s24, v[14:15]
	global_load_dword v152, v[88:89], off nt
	v_or_b32_e32 v86, s4, v36
	v_mad_u64_u32 v[88:89], s[30:31], v86, s24, v[14:15]
	global_load_dword v153, v[88:89], off nt
	v_or_b32_e32 v86, s4, v38
	v_mad_u64_u32 v[88:89], s[30:31], v86, s24, v[14:15]
	global_load_dword v154, v[88:89], off nt
	v_or_b32_e32 v86, s4, v40
	v_mad_u64_u32 v[88:89], s[30:31], v86, s24, v[14:15]
	global_load_dword v155, v[88:89], off nt
	v_or_b32_e32 v86, s4, v42
	v_mad_u64_u32 v[88:89], s[30:31], v86, s24, v[14:15]
	global_load_dword v156, v[88:89], off nt
	v_or_b32_e32 v86, s4, v44
	v_mad_u64_u32 v[88:89], s[30:31], v86, s24, v[14:15]
	global_load_dword v157, v[88:89], off nt
	v_or_b32_e32 v86, s4, v46
	v_mad_u64_u32 v[88:89], s[30:31], v86, s24, v[14:15]
	global_load_dword v158, v[88:89], off nt
	v_or_b32_e32 v86, s4, v48
	v_mad_u64_u32 v[88:89], s[30:31], v86, s24, v[14:15]
	global_load_dword v159, v[88:89], off nt
	v_or_b32_e32 v86, s4, v50
	v_mad_u64_u32 v[88:89], s[30:31], v86, s24, v[14:15]
	global_load_dword v160, v[88:89], off nt
	v_or_b32_e32 v86, s4, v52
	v_mad_u64_u32 v[88:89], s[30:31], v86, s24, v[14:15]
	global_load_dword v161, v[88:89], off nt
	v_or_b32_e32 v86, s4, v54
	v_mad_u64_u32 v[88:89], s[30:31], v86, s24, v[14:15]
	global_load_dword v162, v[88:89], off nt
	v_or_b32_e32 v86, s4, v56
	v_mad_u64_u32 v[88:89], s[30:31], v86, s24, v[14:15]
	global_load_dword v163, v[88:89], off nt
	v_or_b32_e32 v86, s4, v58
	v_mad_u64_u32 v[88:89], s[30:31], v86, s24, v[14:15]
	global_load_dword v164, v[88:89], off nt
	v_or_b32_e32 v86, s4, v60
	v_mad_u64_u32 v[88:89], s[30:31], v86, s24, v[14:15]
	global_load_dword v165, v[88:89], off nt
	v_or_b32_e32 v86, s4, v62
	v_mad_u64_u32 v[88:89], s[30:31], v86, s24, v[14:15]
	global_load_dword v166, v[88:89], off nt
	v_or_b32_e32 v86, s4, v64
	v_mad_u64_u32 v[88:89], s[30:31], v86, s24, v[14:15]
	global_load_dword v167, v[88:89], off nt
	v_or_b32_e32 v86, s4, v66
	v_mad_u64_u32 v[88:89], s[30:31], v86, s24, v[14:15]
	global_load_dword v168, v[88:89], off nt
	v_or_b32_e32 v86, s4, v68
	v_mad_u64_u32 v[88:89], s[30:31], v86, s24, v[14:15]
	global_load_dword v169, v[88:89], off nt
	v_or_b32_e32 v86, s4, v69
	v_mad_u64_u32 v[88:89], s[30:31], v86, s24, v[14:15]
	global_load_dword v170, v[88:89], off nt
	v_or_b32_e32 v86, s4, v70
	v_mad_u64_u32 v[88:89], s[30:31], v86, s24, v[14:15]
	global_load_dword v171, v[88:89], off nt
	v_or_b32_e32 v86, s4, v71
	v_mad_u64_u32 v[88:89], s[30:31], v86, s24, v[14:15]
	global_load_dword v172, v[88:89], off nt
	v_or_b32_e32 v86, s4, v72
	v_mad_u64_u32 v[88:89], s[30:31], v86, s24, v[14:15]
	global_load_dword v173, v[88:89], off nt
	v_or_b32_e32 v86, s4, v73
	v_mad_u64_u32 v[88:89], s[30:31], v86, s24, v[14:15]
	global_load_dword v174, v[88:89], off nt
	v_or_b32_e32 v86, s4, v74
	v_mad_u64_u32 v[88:89], s[30:31], v86, s24, v[14:15]
	global_load_dword v175, v[88:89], off nt
	global_load_dword v176, v85, s[50:51]
	global_load_dword v177, v85, s[50:51] offset:8
	global_load_dword v178, v85, s[50:51] offset:16
	global_load_dword v179, v85, s[50:51] offset:24
	global_load_dword v180, v85, s[50:51] offset:32
	global_load_dword v181, v85, s[50:51] offset:40
	global_load_dword v182, v85, s[50:51] offset:48
	global_load_dword v183, v85, s[50:51] offset:56
	global_load_dword v184, v85, s[50:51] offset:64
	global_load_dword v185, v85, s[50:51] offset:72
	global_load_dword v186, v85, s[50:51] offset:80
	global_load_dword v187, v85, s[50:51] offset:88
	global_load_dword v188, v85, s[50:51] offset:96
	global_load_dword v189, v85, s[50:51] offset:104
	global_load_dword v190, v85, s[50:51] offset:112
	global_load_dword v191, v85, s[50:51] offset:120
	global_load_dword v192, v85, s[50:51] offset:128
	global_load_dword v193, v85, s[50:51] offset:136
	global_load_dword v194, v85, s[50:51] offset:144
	global_load_dword v195, v85, s[50:51] offset:152
	global_load_dword v196, v85, s[50:51] offset:160
	global_load_dword v197, v85, s[50:51] offset:168
	global_load_dword v198, v85, s[50:51] offset:176
	global_load_dword v199, v85, s[50:51] offset:184
	global_load_dword v200, v85, s[50:51] offset:192
	global_load_dword v201, v85, s[50:51] offset:200
	global_load_dword v202, v85, s[50:51] offset:208
	global_load_dword v203, v85, s[50:51] offset:216
	global_load_dword v204, v85, s[50:51] offset:224
	global_load_dword v205, v85, s[50:51] offset:232
	global_load_dword v206, v85, s[50:51] offset:240
	global_load_dword v207, v85, s[50:51] offset:248
	s_waitcnt vmcnt(0)
	v_add_u32_e32 v86, v18, v19
	v_mul_f32_e32 v144, v144, v176
	v_mul_f32_e32 v145, v145, v177
	v_mul_f32_e32 v146, v146, v178
	v_mul_f32_e32 v147, v147, v179
	v_mul_f32_e32 v148, v148, v180
	v_mul_f32_e32 v149, v149, v181
	v_mul_f32_e32 v150, v150, v182
	v_mul_f32_e32 v151, v151, v183
	v_mul_f32_e32 v152, v152, v184
	v_mul_f32_e32 v153, v153, v185
	v_mul_f32_e32 v154, v154, v186
	v_mul_f32_e32 v155, v155, v187
	v_mul_f32_e32 v156, v156, v188
	v_mul_f32_e32 v157, v157, v189
	v_mul_f32_e32 v158, v158, v190
	v_mul_f32_e32 v159, v159, v191
	v_mul_f32_e32 v160, v160, v192
	v_mul_f32_e32 v161, v161, v193
	v_mul_f32_e32 v162, v162, v194
	v_mul_f32_e32 v163, v163, v195
	v_mul_f32_e32 v164, v164, v196
	v_mul_f32_e32 v165, v165, v197
	v_mul_f32_e32 v166, v166, v198
	v_mul_f32_e32 v167, v167, v199
	v_mul_f32_e32 v168, v168, v200
	v_mul_f32_e32 v169, v169, v201
	v_mul_f32_e32 v170, v170, v202
	v_mul_f32_e32 v171, v171, v203
	v_mul_f32_e32 v172, v172, v204
	v_mul_f32_e32 v173, v173, v205
	v_mul_f32_e32 v174, v174, v206
	v_mul_f32_e32 v175, v175, v207
	ds_write_b32 v86, v144
	ds_write_b32 v86, v145 offset:264
	ds_write_b32 v86, v146 offset:528
	ds_write_b32 v86, v147 offset:792
	ds_write_b32 v86, v148 offset:1056
	ds_write_b32 v86, v149 offset:1320
	ds_write_b32 v86, v150 offset:1584
	ds_write_b32 v86, v151 offset:1848
	ds_write_b32 v86, v152 offset:2112
	ds_write_b32 v86, v153 offset:2376
	ds_write_b32 v86, v154 offset:2640
	ds_write_b32 v86, v155 offset:2904
	ds_write_b32 v86, v156 offset:3168
	ds_write_b32 v86, v157 offset:3432
	ds_write_b32 v86, v158 offset:3696
	ds_write_b32 v86, v159 offset:3960
	ds_write_b32 v86, v160 offset:4224
	ds_write_b32 v86, v161 offset:4488
	ds_write_b32 v86, v162 offset:4752
	ds_write_b32 v86, v163 offset:5016
	ds_write_b32 v86, v164 offset:5280
	ds_write_b32 v86, v165 offset:5544
	ds_write_b32 v86, v166 offset:5808
	ds_write_b32 v86, v167 offset:6072
	ds_write_b32 v86, v168 offset:6336
	ds_write_b32 v86, v169 offset:6600
	ds_write_b32 v86, v170 offset:6864
	ds_write_b32 v86, v171 offset:7128
	ds_write_b32 v86, v172 offset:7392
	ds_write_b32 v86, v173 offset:7656
	ds_write_b32 v86, v174 offset:7920
	ds_write_b32 v86, v175 offset:8184
	s_branch .Lq_tail
.Lq_slow:
	v_mad_u64_u32 v[86:87], s[0:1], v84, s24, v[14:15]
	global_load_dword v0, v[86:87], off nt
	v_cmp_ne_u32_e64 s[0:1], 1, v85
	s_andn2_b64 vcc, exec, s[8:9]
	v_readlane_b32 s38, v254, 33
	v_readlane_b32 s39, v254, 34
	v_readlane_b32 s40, v254, 35
	v_readlane_b32 s41, v254, 36
	v_readlane_b32 s42, v254, 37
	v_readlane_b32 s43, v254, 38
	v_readlane_b32 s44, v254, 39
	v_readlane_b32 s45, v254, 40
	v_readlane_b32 s46, v254, 41
	v_readlane_b32 s47, v254, 42
	v_readlane_b32 s48, v254, 43
	v_readlane_b32 s49, v254, 44
	v_readlane_b32 s50, v254, 45
	v_readlane_b32 s51, v254, 46
	s_cbranch_vccnz .LBB0_126
	v_readlane_b32 s36, v254, 3
	v_lshlrev_b32_e32 v84, 2, v84
	v_readlane_b32 s50, v254, 17
	v_readlane_b32 s51, v254, 18
	v_readlane_b32 s37, v254, 4
	v_readlane_b32 s38, v254, 5
	v_readlane_b32 s39, v254, 6
	v_readlane_b32 s40, v254, 7
	v_readlane_b32 s41, v254, 8
	global_load_dword v84, v84, s[50:51]
	v_readlane_b32 s42, v254, 9
	v_readlane_b32 s43, v254, 10
	v_readlane_b32 s44, v254, 11
	v_readlane_b32 s45, v254, 12
	v_readlane_b32 s46, v254, 13
	v_readlane_b32 s47, v254, 14
	v_readlane_b32 s48, v254, 15
	v_readlane_b32 s49, v254, 16
	s_waitcnt vmcnt(0)
	v_mul_f32_e32 v0, v0, v84

.Lq_tail:
	s_waitcnt lgkmcnt(0)
	s_waitcnt vmcnt(0)
	ds_read2_b32 v[14:15], v76 offset0:33 offset1:41
	ds_read2_b32 v[88:89], v76 offset1:8
	ds_read2_b32 v[90:91], v76 offset0:66 offset1:74
	ds_read2_b32 v[92:93], v76 offset0:99 offset1:107
	ds_read2_b32 v[94:95], v76 offset0:132 offset1:140
	ds_read2_b32 v[96:97], v76 offset0:165 offset1:173
	ds_read2_b32 v[98:99], v76 offset0:198 offset1:206
	ds_read2_b32 v[100:101], v76 offset0:231 offset1:239
	v_or_b32_e32 v0, s10, v75
	s_waitcnt lgkmcnt(6)
	v_cvt_pk_bf16_f32 v84, v88, v14
	v_mul_u32_u24_e32 v14, 0xaab, v0
	v_lshrrev_b32_e32 v14, 18, v14
	v_mul_lo_u16_e32 v14, 0x60, v14
	v_sub_u16_e32 v14, v0, v14
	s_waitcnt lgkmcnt(4)
	v_cvt_pk_bf16_f32 v85, v90, v92
	v_cmp_gt_u16_e32 vcc, s25, v14
	v_sub_u32_e32 v90, v0, v14
	v_lshl_add_u32 v90, v14, 1, v90
	v_cndmask_b32_e32 v88, v82, v83, vcc
	s_lshl_b32 s4, s4, 1
	v_add3_u32 v88, v90, v88, 64
	v_cmp_gt_u16_e32 vcc, 64, v14
	v_lshl_add_u64 v[102:103], v[10:11], 0, s[4:5]
	s_waitcnt lgkmcnt(2)
	v_cvt_pk_bf16_f32 v86, v94, v96
	v_cndmask_b32_e32 v0, v88, v0, vcc
	v_mad_i64_i32 v[104:105], s[0:1], v0, s26, v[102:103]
	v_or_b32_e32 v0, s10, v77
	v_mul_u32_u24_e32 v14, 0xaab, v0
	v_lshrrev_b32_e32 v14, 18, v14
	v_mul_lo_u16_e32 v14, 0x60, v14
	v_sub_u16_e32 v14, v0, v14
	s_waitcnt lgkmcnt(0)
	v_cvt_pk_bf16_f32 v87, v98, v100
	v_cmp_gt_u16_e32 vcc, s25, v14
	v_sub_u32_e32 v88, v0, v14
	global_store_dwordx4 v[104:105], v[84:87], off
	v_lshl_add_u32 v88, v14, 1, v88
	s_nop 0
	v_cvt_pk_bf16_f32 v84, v89, v15
	v_cndmask_b32_e32 v15, v82, v83, vcc
	v_add3_u32 v15, v88, v15, 64
	v_cmp_gt_u16_e32 vcc, 64, v14
	v_cvt_pk_bf16_f32 v85, v91, v93
	v_cvt_pk_bf16_f32 v86, v95, v97
	v_cndmask_b32_e32 v0, v15, v0, vcc
	v_cvt_pk_bf16_f32 v87, v99, v101
	v_mad_i64_i32 v[14:15], s[0:1], v0, s26, v[102:103]
	v_or_b32_e32 v0, s10, v78
	ds_read2_b32 v[88:89], v76 offset0:16 offset1:24
	ds_read2_b32 v[90:91], v76 offset0:49 offset1:57
	ds_read2_b32 v[92:93], v76 offset0:82 offset1:90
	ds_read2_b32 v[94:95], v76 offset0:115 offset1:123
	ds_read2_b32 v[96:97], v76 offset0:148 offset1:156
	ds_read2_b32 v[98:99], v76 offset0:181 offset1:189
	ds_read2_b32 v[100:101], v76 offset0:214 offset1:222
	ds_read2_b32 v[104:105], v76 offset0:247 offset1:255
	global_store_dwordx4 v[14:15], v[84:87], off
	v_mul_u32_u24_e32 v14, 0xaab, v0
	v_lshrrev_b32_e32 v14, 18, v14
	v_mul_lo_u16_e32 v14, 0x60, v14
	v_sub_u16_e32 v14, v0, v14
	s_waitcnt lgkmcnt(6)
	v_cvt_pk_bf16_f32 v84, v88, v90
	v_cmp_gt_u16_e32 vcc, s25, v14
	v_sub_u32_e32 v88, v0, v14
	v_lshl_add_u32 v88, v14, 1, v88
	v_cndmask_b32_e32 v15, v82, v83, vcc
	v_add3_u32 v15, v88, v15, 64
	v_cmp_gt_u16_e32 vcc, 64, v14
	s_waitcnt lgkmcnt(4)
	v_cvt_pk_bf16_f32 v85, v92, v94
	s_waitcnt lgkmcnt(2)
	v_cvt_pk_bf16_f32 v86, v96, v98
	v_cndmask_b32_e32 v0, v15, v0, vcc
	s_waitcnt lgkmcnt(0)
	v_cvt_pk_bf16_f32 v87, v100, v104
	v_mad_i64_i32 v[14:15], s[0:1], v0, s26, v[102:103]
	v_or_b32_e32 v0, s10, v79
	global_store_dwordx4 v[14:15], v[84:87], off
	v_mul_u32_u24_e32 v14, 0xaab, v0
	v_lshrrev_b32_e32 v14, 18, v14
	v_mul_lo_u16_e32 v14, 0x60, v14
	v_sub_u16_e32 v14, v0, v14
	v_cmp_gt_u16_e32 vcc, s25, v14
	v_sub_u32_e32 v84, v0, v14
	v_lshl_add_u32 v84, v14, 1, v84
	v_cndmask_b32_e32 v15, v82, v83, vcc
	v_add3_u32 v15, v84, v15, 64
	v_cmp_gt_u16_e32 vcc, 64, v14
	v_cvt_pk_bf16_f32 v84, v89, v91
	v_cvt_pk_bf16_f32 v85, v93, v95
	v_cndmask_b32_e32 v0, v15, v0, vcc
	v_cvt_pk_bf16_f32 v86, v97, v99
	v_cvt_pk_bf16_f32 v87, v101, v105
	v_mad_i64_i32 v[14:15], s[0:1], v0, s26, v[102:103]
	global_store_dwordx4 v[14:15], v[84:87], off
	s_waitcnt lgkmcnt(0)

.LBB0_191:
	s_andn2_b64 vcc, exec, s[0:1]
	s_cbranch_vccnz .LBB0_38
	s_mul_hi_i32 s0, s29, 0x38e38e39
	s_lshr_b32 s1, s0, 31
	s_ashr_i32 s30, s0, 4
	s_add_i32 s30, s30, s1
	s_mul_i32 s4, s30, 0xfffff700
	s_add_i32 s4, s4, s16
	v_add_u32_e32 v0, s4, v16
	v_add_u32_e32 v14, 0x25200, v0
	v_cmp_lt_i32_e32 vcc, s27, v14
	v_add_u32_e32 v0, v18, v19
	s_mov_b64 s[10:11], exec
	v_readlane_b32 s48, v254, 15
	v_readlane_b32 s49, v254, 16
	v_ashrrev_i32_e32 v15, 31, v14
	s_lshl_b32 s0, s30, 6
	v_mov_b32_e32 v144, 0
	v_mov_b32_e32 v145, 0
	v_mov_b32_e32 v146, 0
	v_mov_b32_e32 v147, 0
	v_mov_b32_e32 v148, 0
	v_mov_b32_e32 v149, 0
	v_mov_b32_e32 v150, 0
	v_mov_b32_e32 v151, 0
	v_mov_b32_e32 v152, 0
	v_mov_b32_e32 v153, 0
	v_mov_b32_e32 v154, 0
	v_mov_b32_e32 v155, 0
	v_mov_b32_e32 v156, 0
	v_mov_b32_e32 v157, 0
	v_mov_b32_e32 v158, 0
	v_mov_b32_e32 v159, 0
	v_mov_b32_e32 v160, 0
	v_mov_b32_e32 v161, 0
	v_mov_b32_e32 v162, 0
	v_mov_b32_e32 v163, 0
	v_mov_b32_e32 v164, 0
	v_mov_b32_e32 v165, 0
	v_mov_b32_e32 v166, 0
	v_mov_b32_e32 v167, 0
	v_mov_b32_e32 v168, 0
	v_mov_b32_e32 v169, 0
	v_mov_b32_e32 v170, 0
	v_mov_b32_e32 v171, 0
	v_mov_b32_e32 v172, 0
	v_mov_b32_e32 v173, 0
	v_mov_b32_e32 v174, 0
	v_mov_b32_e32 v175, 0
	v_lshl_add_u64 v[14:15], v[14:15], 2, s[48:49]
	s_andn2_b64 exec, exec, vcc
	v_or_b32_e32 v86, s0, v17
	v_mad_i64_i32 v[88:89], s[30:31], v86, s28, v[14:15]
	global_load_dword v144, v[88:89], off nt
	v_or_b32_e32 v86, s0, v20
	v_mad_i64_i32 v[88:89], s[30:31], v86, s28, v[14:15]
	global_load_dword v145, v[88:89], off nt
	v_or_b32_e32 v86, s0, v22
	v_mad_i64_i32 v[88:89], s[30:31], v86, s28, v[14:15]
	global_load_dword v146, v[88:89], off nt
	v_or_b32_e32 v86, s0, v24
	v_mad_i64_i32 v[88:89], s[30:31], v86, s28, v[14:15]
	global_load_dword v147, v[88:89], off nt
	v_or_b32_e32 v86, s0, v26
	v_mad_i64_i32 v[88:89], s[30:31], v86, s28, v[14:15]
	global_load_dword v148, v[88:89], off nt
	v_or_b32_e32 v86, s0, v28
	v_mad_i64_i32 v[88:89], s[30:31], v86, s28, v[14:15]
	global_load_dword v149, v[88:89], off nt
	v_or_b32_e32 v86, s0, v30
	v_mad_i64_i32 v[88:89], s[30:31], v86, s28, v[14:15]
	global_load_dword v150, v[88:89], off nt
	v_or_b32_e32 v86, s0, v32
	v_mad_i64_i32 v[88:89], s[30:31], v86, s28, v[14:15]
	global_load_dword v151, v[88:89], off nt
	v_or_b32_e32 v86, s0, v34
	v_mad_i64_i32 v[88:89], s[30:31], v86, s28, v[14:15]
	global_load_dword v152, v[88:89], off nt
	v_or_b32_e32 v86, s0, v36
	v_mad_i64_i32 v[88:89], s[30:31], v86, s28, v[14:15]
	global_load_dword v153, v[88:89], off nt
	v_or_b32_e32 v86, s0, v38
	v_mad_i64_i32 v[88:89], s[30:31], v86, s28, v[14:15]
	global_load_dword v154, v[88:89], off nt
	v_or_b32_e32 v86, s0, v40
	v_mad_i64_i32 v[88:89], s[30:31], v86, s28, v[14:15]
	global_load_dword v155, v[88:89], off nt
	v_or_b32_e32 v86, s0, v42
	v_mad_i64_i32 v[88:89], s[30:31], v86, s28, v[14:15]
	global_load_dword v156, v[88:89], off nt
	v_or_b32_e32 v86, s0, v44
	v_mad_i64_i32 v[88:89], s[30:31], v86, s28, v[14:15]
	global_load_dword v157, v[88:89], off nt
	v_or_b32_e32 v86, s0, v46
	v_mad_i64_i32 v[88:89], s[30:31], v86, s28, v[14:15]
	global_load_dword v158, v[88:89], off nt
	v_or_b32_e32 v86, s0, v48
	v_mad_i64_i32 v[88:89], s[30:31], v86, s28, v[14:15]
	global_load_dword v159, v[88:89], off nt
	v_or_b32_e32 v86, s0, v50
	v_mad_i64_i32 v[88:89], s[30:31], v86, s28, v[14:15]
	global_load_dword v160, v[88:89], off nt
	v_or_b32_e32 v86, s0, v52
	v_mad_i64_i32 v[88:89], s[30:31], v86, s28, v[14:15]
	global_load_dword v161, v[88:89], off nt
	v_or_b32_e32 v86, s0, v54
	v_mad_i64_i32 v[88:89], s[30:31], v86, s28, v[14:15]
	global_load_dword v162, v[88:89], off nt
	v_or_b32_e32 v86, s0, v56
	v_mad_i64_i32 v[88:89], s[30:31], v86, s28, v[14:15]
	global_load_dword v163, v[88:89], off nt
	v_or_b32_e32 v86, s0, v58
	v_mad_i64_i32 v[88:89], s[30:31], v86, s28, v[14:15]
	global_load_dword v164, v[88:89], off nt
	v_or_b32_e32 v86, s0, v60
	v_mad_i64_i32 v[88:89], s[30:31], v86, s28, v[14:15]
	global_load_dword v165, v[88:89], off nt
	v_or_b32_e32 v86, s0, v62
	v_mad_i64_i32 v[88:89], s[30:31], v86, s28, v[14:15]
	global_load_dword v166, v[88:89], off nt
	v_or_b32_e32 v86, s0, v64
	v_mad_i64_i32 v[88:89], s[30:31], v86, s28, v[14:15]
	global_load_dword v167, v[88:89], off nt
	v_or_b32_e32 v86, s0, v66
	v_mad_i64_i32 v[88:89], s[30:31], v86, s28, v[14:15]
	global_load_dword v168, v[88:89], off nt
	v_or_b32_e32 v86, s0, v68
	v_mad_i64_i32 v[88:89], s[30:31], v86, s28, v[14:15]
	global_load_dword v169, v[88:89], off nt
	v_or_b32_e32 v86, s0, v69
	v_mad_i64_i32 v[88:89], s[30:31], v86, s28, v[14:15]
	global_load_dword v170, v[88:89], off nt
	v_or_b32_e32 v86, s0, v70
	v_mad_i64_i32 v[88:89], s[30:31], v86, s28, v[14:15]
	global_load_dword v171, v[88:89], off nt
	v_or_b32_e32 v86, s0, v71
	v_mad_i64_i32 v[88:89], s[30:31], v86, s28, v[14:15]
	global_load_dword v172, v[88:89], off nt
	v_or_b32_e32 v86, s0, v72
	v_mad_i64_i32 v[88:89], s[30:31], v86, s28, v[14:15]
	global_load_dword v173, v[88:89], off nt
	v_or_b32_e32 v86, s0, v73
	v_mad_i64_i32 v[88:89], s[30:31], v86, s28, v[14:15]
	global_load_dword v174, v[88:89], off nt
	v_or_b32_e32 v86, s0, v74
	v_mad_i64_i32 v[88:89], s[30:31], v86, s28, v[14:15]
	global_load_dword v175, v[88:89], off nt
	s_mov_b64 exec, s[10:11]
	s_waitcnt vmcnt(0)
	v_add_u32_e32 v86, v18, v19
	ds_write_b32 v86, v144
	ds_write_b32 v86, v145 offset:264
	ds_write_b32 v86, v146 offset:528
	ds_write_b32 v86, v147 offset:792
	ds_write_b32 v86, v148 offset:1056
	ds_write_b32 v86, v149 offset:1320
	ds_write_b32 v86, v150 offset:1584
	ds_write_b32 v86, v151 offset:1848
	ds_write_b32 v86, v152 offset:2112
	ds_write_b32 v86, v153 offset:2376
	ds_write_b32 v86, v154 offset:2640
	ds_write_b32 v86, v155 offset:2904
	ds_write_b32 v86, v156 offset:3168
	ds_write_b32 v86, v157 offset:3432
	ds_write_b32 v86, v158 offset:3696
	ds_write_b32 v86, v159 offset:3960
	ds_write_b32 v86, v160 offset:4224
	ds_write_b32 v86, v161 offset:4488
	ds_write_b32 v86, v162 offset:4752
	ds_write_b32 v86, v163 offset:5016
	ds_write_b32 v86, v164 offset:5280
	ds_write_b32 v86, v165 offset:5544
	ds_write_b32 v86, v166 offset:5808
	ds_write_b32 v86, v167 offset:6072
	ds_write_b32 v86, v168 offset:6336
	ds_write_b32 v86, v169 offset:6600
	ds_write_b32 v86, v170 offset:6864
	ds_write_b32 v86, v171 offset:7128
	ds_write_b32 v86, v172 offset:7392
	ds_write_b32 v86, v173 offset:7656
	ds_write_b32 v86, v174 offset:7920
	ds_write_b32 v86, v175 offset:8184
	s_branch .Lin_tail

.LBB0_547:
	s_lshl_b32 s0, s47, 8
	v_readlane_b32 s1, v254, 61
	s_add_i32 s0, s0, s1
	v_mbcnt_lo_u32_b32 v136, -1, 0
	v_mbcnt_hi_u32_b32 v136, -1, v136
	v_mov_b32_e32 v140, s0
	v_and_b32_e32 v139, 15, v136
	s_movk_i32 s1, 0xfcf
	v_or_b32_e32 v138, s0, v139
	v_bitop3_b32 v154, v139, s1, v140 bitop3:0xc8
	v_lshrrev_b32_e32 v139, 1, v136
	v_readlane_b32 s1, v255, 44
	s_ashr_i32 s0, s0, 9
	v_lshlrev_b32_e32 v140, 1, v136
	v_and_or_b32 v155, v139, 24, s1
	s_lshl_b32 s1, s28, 1
	s_and_b32 s23, s0, -8
	v_and_b32_e32 v140, 8, v140
	v_and_b32_e32 v139, 4, v139
	v_and_b32_e32 v136, 3, v136
	s_add_i32 s23, s23, s1
	v_lshrrev_b32_e32 v156, 5, v154
	v_or3_b32 v139, v139, v136, v140
	v_lshl_or_b32 v140, s23, 7, v156
	v_ashrrev_i32_e32 v141, 31, v140
	v_readlane_b32 s0, v255, 49
	v_lshlrev_b64 v[140:141], 12, v[140:141]
	v_readlane_b32 s1, v255, 50
	v_lshlrev_b32_e32 v136, 6, v155
	s_and_b64 vcc, exec, s[2:3]
	v_lshl_add_u64 v[140:141], s[0:1], 0, v[140:141]
	v_lshl_add_u64 v[140:141], v[140:141], 0, v[136:137]
	v_lshlrev_b32_e32 v136, 1, v139
	v_ashrrev_i32_e32 v139, 31, v138
	v_lshl_add_u64 v[142:143], v[138:139], 2, s[16:17]
	global_load_dword v200, v[142:143], off
	global_load_dword v201, v[142:143], off offset:64
	global_load_dword v202, v[142:143], off offset:128
	global_load_dword v203, v[142:143], off offset:192
	global_load_dword v204, v[142:143], off offset:512
	global_load_dword v205, v[142:143], off offset:576
	global_load_dword v206, v[142:143], off offset:640
	global_load_dword v207, v[142:143], off offset:704
	v_lshl_add_u64 v[144:145], v[140:141], 0, v[136:137]
	s_mov_b64 s[0:1], -1
	s_waitcnt vmcnt(0)
	v_mov_b32_e32 v138, v200
	v_pk_mul_f32 v[146:147], v[122:123], v[138:139] op_sel_hi:[1,0]
	v_pk_mul_f32 v[148:149], v[120:121], v[138:139] op_sel_hi:[1,0]
	v_pk_mul_f32 v[126:127], v[126:127], v[138:139] op_sel_hi:[1,0]
	v_pk_mul_f32 v[124:125], v[124:125], v[138:139] op_sel_hi:[1,0]
	s_cbranch_vccz .LBB0_549
	v_cvt_pk_bf16_f32 v120, v148, s0
	global_store_short v[144:145], v120, off offset:-4096
	v_cvt_pk_bf16_f32 v120, v149, s0
	global_store_short v[144:145], v120, off offset:-4032
	v_cvt_pk_bf16_f32 v120, v146, s0
	global_store_short v[144:145], v120, off offset:-3968
	v_cvt_pk_bf16_f32 v120, v147, s0
	global_store_short v[144:145], v120, off offset:-3904
	v_cvt_pk_bf16_f32 v120, v124, s0
	global_store_short v[144:145], v120, off offset:-3840
	v_cvt_pk_bf16_f32 v120, v125, s0
	global_store_short v[144:145], v120, off offset:-3776
	v_cvt_pk_bf16_f32 v120, v126, s0
	global_store_short v[144:145], v120, off offset:-3712
	v_cvt_pk_bf16_f32 v120, v127, s0
	global_store_short v[144:145], v120, off offset:-3648
	s_mov_b64 s[0:1], 0

.LBB0_551:
	v_mov_b32_e32 v126, v201
	v_cndmask_b32_e64 v121, 0, 1, s[2:3]
	v_cmp_ne_u32_e64 s[0:1], 1, v121
	s_andn2_b64 vcc, exec, s[2:3]
	s_mov_b64 s[28:29], -1
	v_pk_mul_f32 v[114:115], v[114:115], v[126:127] op_sel_hi:[1,0]
	v_pk_mul_f32 v[124:125], v[112:113], v[126:127] op_sel_hi:[1,0]
	v_pk_mul_f32 v[112:113], v[118:119], v[126:127] op_sel_hi:[1,0]
	v_pk_mul_f32 v[116:117], v[116:117], v[126:127] op_sel_hi:[1,0]
	s_cbranch_vccnz .LBB0_553
	v_cvt_pk_bf16_f32 v118, v124, s0
	global_store_short v[144:145], v118, off offset:-4064
	v_cvt_pk_bf16_f32 v118, v125, s0
	global_store_short v[144:145], v118, off offset:-4000
	v_cvt_pk_bf16_f32 v118, v114, s0
	global_store_short v[144:145], v118, off offset:-3936
	v_cvt_pk_bf16_f32 v118, v115, s0
	global_store_short v[144:145], v118, off offset:-3872
	v_cvt_pk_bf16_f32 v118, v116, s0
	global_store_short v[144:145], v118, off offset:-3808
	v_cvt_pk_bf16_f32 v118, v117, s0
	global_store_short v[144:145], v118, off offset:-3744
	v_cvt_pk_bf16_f32 v118, v112, s0
	global_store_short v[144:145], v118, off offset:-3680
	v_cvt_pk_bf16_f32 v118, v113, s0
	s_mov_b64 s[28:29], 0
	global_store_short v[144:145], v118, off offset:-3616

.LBB0_555:
	v_mov_b32_e32 v114, v202
	s_and_b64 vcc, exec, s[0:1]
	s_mov_b64 s[28:29], -1
	v_pk_mul_f32 v[106:107], v[106:107], v[114:115] op_sel_hi:[1,0]
	v_pk_mul_f32 v[112:113], v[104:105], v[114:115] op_sel_hi:[1,0]
	v_pk_mul_f32 v[104:105], v[110:111], v[114:115] op_sel_hi:[1,0]
	v_pk_mul_f32 v[108:109], v[108:109], v[114:115] op_sel_hi:[1,0]
	s_cbranch_vccnz .LBB0_557
	v_cvt_pk_bf16_f32 v110, v112, s0
	global_store_short v[144:145], v110, off
	v_cvt_pk_bf16_f32 v110, v113, s0
	global_store_short v[144:145], v110, off offset:64
	v_cvt_pk_bf16_f32 v110, v106, s0
	global_store_short v[144:145], v110, off offset:128
	v_cvt_pk_bf16_f32 v110, v107, s0
	global_store_short v[144:145], v110, off offset:192
	v_cvt_pk_bf16_f32 v110, v108, s0
	global_store_short v[144:145], v110, off offset:256
	v_cvt_pk_bf16_f32 v110, v109, s0
	global_store_short v[144:145], v110, off offset:320
	v_cvt_pk_bf16_f32 v110, v104, s0
	global_store_short v[144:145], v110, off offset:384
	v_cvt_pk_bf16_f32 v110, v105, s0
	s_mov_b64 s[28:29], 0
	global_store_short v[144:145], v110, off offset:448

.LBB0_559:
	v_mov_b32_e32 v106, v203
	s_and_b64 vcc, exec, s[0:1]
	s_mov_b64 s[28:29], -1
	v_pk_mul_f32 v[98:99], v[98:99], v[106:107] op_sel_hi:[1,0]
	v_pk_mul_f32 v[104:105], v[96:97], v[106:107] op_sel_hi:[1,0]
	v_pk_mul_f32 v[96:97], v[102:103], v[106:107] op_sel_hi:[1,0]
	v_pk_mul_f32 v[100:101], v[100:101], v[106:107] op_sel_hi:[1,0]
	s_cbranch_vccnz .LBB0_561
	v_cvt_pk_bf16_f32 v102, v104, s0
	global_store_short v[144:145], v102, off offset:32
	v_cvt_pk_bf16_f32 v102, v105, s0
	global_store_short v[144:145], v102, off offset:96
	v_cvt_pk_bf16_f32 v102, v98, s0
	global_store_short v[144:145], v102, off offset:160
	v_cvt_pk_bf16_f32 v102, v99, s0
	global_store_short v[144:145], v102, off offset:224
	v_cvt_pk_bf16_f32 v102, v100, s0
	global_store_short v[144:145], v102, off offset:288
	v_cvt_pk_bf16_f32 v102, v101, s0
	global_store_short v[144:145], v102, off offset:352
	v_cvt_pk_bf16_f32 v102, v96, s0
	global_store_short v[144:145], v102, off offset:416
	v_cvt_pk_bf16_f32 v102, v97, s0
	s_mov_b64 s[28:29], 0
	global_store_short v[144:145], v102, off offset:480

.LBB0_563:
	v_mov_b32_e32 v100, v204
	v_lshl_add_u64 v[96:97], v[144:145], 0, s[20:21]
	s_and_b64 vcc, exec, s[0:1]
	s_mov_b64 s[28:29], -1
	v_pk_mul_f32 v[90:91], v[90:91], v[100:101] op_sel_hi:[1,0]
	v_pk_mul_f32 v[98:99], v[88:89], v[100:101] op_sel_hi:[1,0]
	v_pk_mul_f32 v[88:89], v[94:95], v[100:101] op_sel_hi:[1,0]
	v_pk_mul_f32 v[92:93], v[92:93], v[100:101] op_sel_hi:[1,0]
	s_cbranch_vccnz .LBB0_565
	v_add_co_u32_e32 v94, vcc, 0x4000, v96
	v_cvt_pk_bf16_f32 v100, v98, s0
	s_nop 0
	v_addc_co_u32_e32 v95, vcc, 0, v97, vcc
	global_store_short v[94:95], v100, off
	v_cvt_pk_bf16_f32 v100, v99, s0
	global_store_short v[94:95], v100, off offset:64
	v_cvt_pk_bf16_f32 v100, v90, s0
	global_store_short v[94:95], v100, off offset:128
	v_cvt_pk_bf16_f32 v100, v91, s0
	global_store_short v[94:95], v100, off offset:192
	v_cvt_pk_bf16_f32 v100, v92, s0
	global_store_short v[94:95], v100, off offset:256
	v_cvt_pk_bf16_f32 v100, v93, s0
	global_store_short v[94:95], v100, off offset:320
	v_cvt_pk_bf16_f32 v100, v88, s0
	global_store_short v[94:95], v100, off offset:384
	v_cvt_pk_bf16_f32 v100, v89, s0
	s_mov_b64 s[28:29], 0
	global_store_short v[94:95], v100, off offset:448

.LBB0_567:
	v_mov_b32_e32 v90, v205
	s_and_b64 vcc, exec, s[0:1]
	s_mov_b64 s[28:29], -1
	v_pk_mul_f32 v[82:83], v[82:83], v[90:91] op_sel_hi:[1,0]
	v_pk_mul_f32 v[88:89], v[80:81], v[90:91] op_sel_hi:[1,0]
	v_pk_mul_f32 v[80:81], v[86:87], v[90:91] op_sel_hi:[1,0]
	v_pk_mul_f32 v[84:85], v[84:85], v[90:91] op_sel_hi:[1,0]
	s_cbranch_vccnz .LBB0_569
	v_add_co_u32_e32 v86, vcc, 0x4000, v96
	v_cvt_pk_bf16_f32 v90, v88, s0
	s_nop 0
	v_addc_co_u32_e32 v87, vcc, 0, v97, vcc
	global_store_short v[86:87], v90, off offset:32
	v_cvt_pk_bf16_f32 v90, v89, s0
	global_store_short v[86:87], v90, off offset:96
	v_cvt_pk_bf16_f32 v90, v82, s0
	global_store_short v[86:87], v90, off offset:160
	v_cvt_pk_bf16_f32 v90, v83, s0
	global_store_short v[86:87], v90, off offset:224
	v_cvt_pk_bf16_f32 v90, v84, s0
	global_store_short v[86:87], v90, off offset:288
	v_cvt_pk_bf16_f32 v90, v85, s0
	global_store_short v[86:87], v90, off offset:352
	v_cvt_pk_bf16_f32 v90, v80, s0
	global_store_short v[86:87], v90, off offset:416
	v_cvt_pk_bf16_f32 v90, v81, s0
	s_mov_b64 s[28:29], 0
	global_store_short v[86:87], v90, off offset:480

.LBB0_571:
	v_mov_b32_e32 v82, v206
	s_and_b64 vcc, exec, s[0:1]
	s_mov_b64 s[28:29], -1
	v_pk_mul_f32 v[74:75], v[74:75], v[82:83] op_sel_hi:[1,0]
	v_pk_mul_f32 v[80:81], v[72:73], v[82:83] op_sel_hi:[1,0]
	v_pk_mul_f32 v[72:73], v[78:79], v[82:83] op_sel_hi:[1,0]
	v_pk_mul_f32 v[76:77], v[76:77], v[82:83] op_sel_hi:[1,0]
	s_cbranch_vccnz .LBB0_573
	v_add_co_u32_e32 v78, vcc, 0x5000, v96
	v_cvt_pk_bf16_f32 v82, v80, s0
	s_nop 0
	v_addc_co_u32_e32 v79, vcc, 0, v97, vcc
	global_store_short v[78:79], v82, off
	v_cvt_pk_bf16_f32 v82, v81, s0
	global_store_short v[78:79], v82, off offset:64
	v_cvt_pk_bf16_f32 v82, v74, s0
	global_store_short v[78:79], v82, off offset:128
	v_cvt_pk_bf16_f32 v82, v75, s0
	global_store_short v[78:79], v82, off offset:192
	v_cvt_pk_bf16_f32 v82, v76, s0
	global_store_short v[78:79], v82, off offset:256
	v_cvt_pk_bf16_f32 v82, v77, s0
	global_store_short v[78:79], v82, off offset:320
	v_cvt_pk_bf16_f32 v82, v72, s0
	global_store_short v[78:79], v82, off offset:384
	v_cvt_pk_bf16_f32 v82, v73, s0
	s_mov_b64 s[28:29], 0
	global_store_short v[78:79], v82, off offset:448

.LBB0_575:
	v_mov_b32_e32 v74, v207
	s_and_b64 vcc, exec, s[0:1]
	s_mov_b64 s[28:29], -1
	v_pk_mul_f32 v[66:67], v[66:67], v[74:75] op_sel_hi:[1,0]
	v_pk_mul_f32 v[72:73], v[64:65], v[74:75] op_sel_hi:[1,0]
	v_pk_mul_f32 v[64:65], v[70:71], v[74:75] op_sel_hi:[1,0]
	v_pk_mul_f32 v[68:69], v[68:69], v[74:75] op_sel_hi:[1,0]
	s_cbranch_vccnz .LBB0_577
	v_add_co_u32_e32 v70, vcc, 0x5000, v96
	v_cvt_pk_bf16_f32 v74, v72, s0
	s_nop 0
	v_addc_co_u32_e32 v71, vcc, 0, v97, vcc
	global_store_short v[70:71], v74, off offset:32
	v_cvt_pk_bf16_f32 v74, v73, s0
	global_store_short v[70:71], v74, off offset:96
	v_cvt_pk_bf16_f32 v74, v66, s0
	global_store_short v[70:71], v74, off offset:160
	v_cvt_pk_bf16_f32 v74, v67, s0
	global_store_short v[70:71], v74, off offset:224
	v_cvt_pk_bf16_f32 v74, v68, s0
	global_store_short v[70:71], v74, off offset:288
	v_cvt_pk_bf16_f32 v74, v69, s0
	global_store_short v[70:71], v74, off offset:352
	v_cvt_pk_bf16_f32 v74, v64, s0
	global_store_short v[70:71], v74, off offset:416
	v_cvt_pk_bf16_f32 v74, v65, s0
	s_mov_b64 s[28:29], 0
	global_store_short v[70:71], v74, off offset:480

.LBB0_579:
	v_mov_b32_e32 v68, v200
	s_or_b32 s23, s23, 1
	v_lshl_or_b32 v64, s23, 7, v156
	v_ashrrev_i32_e32 v65, 31, v64
	v_readlane_b32 s28, v255, 49
	v_lshlrev_b32_e32 v66, 5, v155
	v_lshlrev_b64 v[64:65], 12, v[64:65]
	v_readlane_b32 s29, v255, 50
	v_lshlrev_b32_e32 v66, 1, v66
	v_mov_b32_e32 v67, v137
	v_lshl_add_u64 v[64:65], s[28:29], 0, v[64:65]
	v_lshl_add_u64 v[64:65], v[64:65], 0, v[66:67]
	v_lshl_add_u64 v[64:65], v[64:65], 0, v[136:137]
	s_mov_b64 s[28:29], -1
	s_and_b64 vcc, exec, s[0:1]
	v_pk_mul_f32 v[58:59], v[58:59], v[68:69] op_sel_hi:[1,0]
	v_pk_mul_f32 v[66:67], v[56:57], v[68:69] op_sel_hi:[1,0]
	v_pk_mul_f32 v[62:63], v[62:63], v[68:69] op_sel_hi:[1,0]
	v_pk_mul_f32 v[60:61], v[60:61], v[68:69] op_sel_hi:[1,0]
	s_cbranch_vccnz .LBB0_581
	v_cvt_pk_bf16_f32 v56, v66, s0
	global_store_short v[64:65], v56, off offset:-4096
	v_cvt_pk_bf16_f32 v56, v67, s0
	global_store_short v[64:65], v56, off offset:-4032
	v_cvt_pk_bf16_f32 v56, v58, s0
	global_store_short v[64:65], v56, off offset:-3968
	v_cvt_pk_bf16_f32 v56, v59, s0
	global_store_short v[64:65], v56, off offset:-3904
	v_cvt_pk_bf16_f32 v56, v60, s0
	global_store_short v[64:65], v56, off offset:-3840
	v_cvt_pk_bf16_f32 v56, v61, s0
	global_store_short v[64:65], v56, off offset:-3776
	v_cvt_pk_bf16_f32 v56, v62, s0
	global_store_short v[64:65], v56, off offset:-3712
	v_cvt_pk_bf16_f32 v56, v63, s0
	s_mov_b64 s[28:29], 0
	global_store_short v[64:65], v56, off offset:-3648

.LBB0_583:
	v_mov_b32_e32 v60, v201
	s_and_b64 vcc, exec, s[0:1]
	s_mov_b64 s[28:29], -1
	v_pk_mul_f32 v[50:51], v[50:51], v[60:61] op_sel_hi:[1,0]
	v_pk_mul_f32 v[58:59], v[48:49], v[60:61] op_sel_hi:[1,0]
	v_pk_mul_f32 v[48:49], v[54:55], v[60:61] op_sel_hi:[1,0]
	v_pk_mul_f32 v[52:53], v[52:53], v[60:61] op_sel_hi:[1,0]
	s_cbranch_vccnz .LBB0_585
	v_cvt_pk_bf16_f32 v54, v58, s0
	global_store_short v[64:65], v54, off offset:-4064
	v_cvt_pk_bf16_f32 v54, v59, s0
	global_store_short v[64:65], v54, off offset:-4000
	v_cvt_pk_bf16_f32 v54, v50, s0
	global_store_short v[64:65], v54, off offset:-3936
	v_cvt_pk_bf16_f32 v54, v51, s0
	global_store_short v[64:65], v54, off offset:-3872
	v_cvt_pk_bf16_f32 v54, v52, s0
	global_store_short v[64:65], v54, off offset:-3808
	v_cvt_pk_bf16_f32 v54, v53, s0
	global_store_short v[64:65], v54, off offset:-3744
	v_cvt_pk_bf16_f32 v54, v48, s0
	global_store_short v[64:65], v54, off offset:-3680
	v_cvt_pk_bf16_f32 v54, v49, s0
	s_mov_b64 s[28:29], 0
	global_store_short v[64:65], v54, off offset:-3616

.LBB0_587:
	v_mov_b32_e32 v50, v202
	s_and_b64 vcc, exec, s[0:1]
	s_mov_b64 s[28:29], -1
	v_pk_mul_f32 v[42:43], v[42:43], v[50:51] op_sel_hi:[1,0]
	v_pk_mul_f32 v[48:49], v[40:41], v[50:51] op_sel_hi:[1,0]
	v_pk_mul_f32 v[40:41], v[46:47], v[50:51] op_sel_hi:[1,0]
	v_pk_mul_f32 v[44:45], v[44:45], v[50:51] op_sel_hi:[1,0]
	s_cbranch_vccnz .LBB0_589
	v_cvt_pk_bf16_f32 v46, v48, s0
	global_store_short v[64:65], v46, off
	v_cvt_pk_bf16_f32 v46, v49, s0
	global_store_short v[64:65], v46, off offset:64
	v_cvt_pk_bf16_f32 v46, v42, s0
	global_store_short v[64:65], v46, off offset:128
	v_cvt_pk_bf16_f32 v46, v43, s0
	global_store_short v[64:65], v46, off offset:192
	v_cvt_pk_bf16_f32 v46, v44, s0
	global_store_short v[64:65], v46, off offset:256
	v_cvt_pk_bf16_f32 v46, v45, s0
	global_store_short v[64:65], v46, off offset:320
	v_cvt_pk_bf16_f32 v46, v40, s0
	global_store_short v[64:65], v46, off offset:384
	v_cvt_pk_bf16_f32 v46, v41, s0
	s_mov_b64 s[28:29], 0
	global_store_short v[64:65], v46, off offset:448

.LBB0_591:
	v_mov_b32_e32 v42, v203
	s_and_b64 vcc, exec, s[0:1]
	s_mov_b64 s[28:29], -1
	v_pk_mul_f32 v[34:35], v[34:35], v[42:43] op_sel_hi:[1,0]
	v_pk_mul_f32 v[40:41], v[32:33], v[42:43] op_sel_hi:[1,0]
	v_pk_mul_f32 v[32:33], v[38:39], v[42:43] op_sel_hi:[1,0]
	v_pk_mul_f32 v[36:37], v[36:37], v[42:43] op_sel_hi:[1,0]
	s_cbranch_vccnz .LBB0_593
	v_cvt_pk_bf16_f32 v38, v40, s0
	global_store_short v[64:65], v38, off offset:32
	v_cvt_pk_bf16_f32 v38, v41, s0
	global_store_short v[64:65], v38, off offset:96
	v_cvt_pk_bf16_f32 v38, v34, s0
	global_store_short v[64:65], v38, off offset:160
	v_cvt_pk_bf16_f32 v38, v35, s0
	global_store_short v[64:65], v38, off offset:224
	v_cvt_pk_bf16_f32 v38, v36, s0
	global_store_short v[64:65], v38, off offset:288
	v_cvt_pk_bf16_f32 v38, v37, s0
	global_store_short v[64:65], v38, off offset:352
	v_cvt_pk_bf16_f32 v38, v32, s0
	global_store_short v[64:65], v38, off offset:416
	v_cvt_pk_bf16_f32 v38, v33, s0
	s_mov_b64 s[28:29], 0
	global_store_short v[64:65], v38, off offset:480

.LBB0_595:
	v_mov_b32_e32 v36, v204
	v_lshl_add_u64 v[32:33], v[64:65], 0, s[20:21]
	s_and_b64 vcc, exec, s[0:1]
	s_mov_b64 s[28:29], -1
	v_pk_mul_f32 v[26:27], v[26:27], v[36:37] op_sel_hi:[1,0]
	v_pk_mul_f32 v[34:35], v[24:25], v[36:37] op_sel_hi:[1,0]
	v_pk_mul_f32 v[24:25], v[30:31], v[36:37] op_sel_hi:[1,0]
	v_pk_mul_f32 v[28:29], v[28:29], v[36:37] op_sel_hi:[1,0]
	s_cbranch_vccnz .LBB0_597
	v_add_co_u32_e32 v30, vcc, 0x4000, v32
	v_cvt_pk_bf16_f32 v36, v34, s0
	s_nop 0
	v_addc_co_u32_e32 v31, vcc, 0, v33, vcc
	global_store_short v[30:31], v36, off
	v_cvt_pk_bf16_f32 v36, v35, s0
	global_store_short v[30:31], v36, off offset:64
	v_cvt_pk_bf16_f32 v36, v26, s0
	global_store_short v[30:31], v36, off offset:128
	v_cvt_pk_bf16_f32 v36, v27, s0
	global_store_short v[30:31], v36, off offset:192
	v_cvt_pk_bf16_f32 v36, v28, s0
	global_store_short v[30:31], v36, off offset:256
	v_cvt_pk_bf16_f32 v36, v29, s0
	global_store_short v[30:31], v36, off offset:320
	v_cvt_pk_bf16_f32 v36, v24, s0
	global_store_short v[30:31], v36, off offset:384
	v_cvt_pk_bf16_f32 v36, v25, s0
	s_mov_b64 s[28:29], 0
	global_store_short v[30:31], v36, off offset:448

.LBB0_599:
	v_mov_b32_e32 v26, v205
	s_and_b64 vcc, exec, s[0:1]
	s_mov_b64 s[28:29], -1
	v_pk_mul_f32 v[18:19], v[18:19], v[26:27] op_sel_hi:[1,0]
	v_pk_mul_f32 v[24:25], v[16:17], v[26:27] op_sel_hi:[1,0]
	v_pk_mul_f32 v[16:17], v[22:23], v[26:27] op_sel_hi:[1,0]
	v_pk_mul_f32 v[20:21], v[20:21], v[26:27] op_sel_hi:[1,0]
	s_cbranch_vccnz .LBB0_601
	v_add_co_u32_e32 v22, vcc, 0x4000, v32
	v_cvt_pk_bf16_f32 v26, v24, s0
	s_nop 0
	v_addc_co_u32_e32 v23, vcc, 0, v33, vcc
	global_store_short v[22:23], v26, off offset:32
	v_cvt_pk_bf16_f32 v26, v25, s0
	global_store_short v[22:23], v26, off offset:96
	v_cvt_pk_bf16_f32 v26, v18, s0
	global_store_short v[22:23], v26, off offset:160
	v_cvt_pk_bf16_f32 v26, v19, s0
	global_store_short v[22:23], v26, off offset:224
	v_cvt_pk_bf16_f32 v26, v20, s0
	global_store_short v[22:23], v26, off offset:288
	v_cvt_pk_bf16_f32 v26, v21, s0
	global_store_short v[22:23], v26, off offset:352
	v_cvt_pk_bf16_f32 v26, v16, s0
	global_store_short v[22:23], v26, off offset:416
	v_cvt_pk_bf16_f32 v26, v17, s0
	s_mov_b64 s[28:29], 0
	global_store_short v[22:23], v26, off offset:480

.LBB0_603:
	v_mov_b32_e32 v18, v206
	s_and_b64 vcc, exec, s[0:1]
	s_mov_b64 s[28:29], -1
	v_pk_mul_f32 v[10:11], v[10:11], v[18:19] op_sel_hi:[1,0]
	v_pk_mul_f32 v[16:17], v[8:9], v[18:19] op_sel_hi:[1,0]
	v_pk_mul_f32 v[8:9], v[14:15], v[18:19] op_sel_hi:[1,0]
	v_pk_mul_f32 v[12:13], v[12:13], v[18:19] op_sel_hi:[1,0]
	s_cbranch_vccnz .LBB0_605
	v_add_co_u32_e32 v14, vcc, 0x5000, v32
	v_cvt_pk_bf16_f32 v18, v16, s0
	s_nop 0
	v_addc_co_u32_e32 v15, vcc, 0, v33, vcc
	global_store_short v[14:15], v18, off
	v_cvt_pk_bf16_f32 v18, v17, s0
	global_store_short v[14:15], v18, off offset:64
	v_cvt_pk_bf16_f32 v18, v10, s0
	global_store_short v[14:15], v18, off offset:128
	v_cvt_pk_bf16_f32 v18, v11, s0
	global_store_short v[14:15], v18, off offset:192
	v_cvt_pk_bf16_f32 v18, v12, s0
	global_store_short v[14:15], v18, off offset:256
	v_cvt_pk_bf16_f32 v18, v13, s0
	global_store_short v[14:15], v18, off offset:320
	v_cvt_pk_bf16_f32 v18, v8, s0
	global_store_short v[14:15], v18, off offset:384
	v_cvt_pk_bf16_f32 v18, v9, s0
	s_mov_b64 s[28:29], 0
	global_store_short v[14:15], v18, off offset:448

.LBB0_607:
	v_mov_b32_e32 v10, v207
	s_and_b64 vcc, exec, s[0:1]
	s_mov_b64 s[0:1], -1
	v_pk_mul_f32 v[2:3], v[2:3], v[10:11] op_sel_hi:[1,0]
	v_pk_mul_f32 v[8:9], v[0:1], v[10:11] op_sel_hi:[1,0]
	v_pk_mul_f32 v[0:1], v[6:7], v[10:11] op_sel_hi:[1,0]
	v_pk_mul_f32 v[4:5], v[4:5], v[10:11] op_sel_hi:[1,0]
	s_cbranch_vccnz .LBB0_609
	v_add_co_u32_e32 v6, vcc, 0x5000, v32
	v_cvt_pk_bf16_f32 v10, v8, s0
	s_nop 0
	v_addc_co_u32_e32 v7, vcc, 0, v33, vcc
	global_store_short v[6:7], v10, off offset:32
	v_cvt_pk_bf16_f32 v10, v9, s0
	global_store_short v[6:7], v10, off offset:96
	v_cvt_pk_bf16_f32 v10, v2, s0
	global_store_short v[6:7], v10, off offset:160
	v_cvt_pk_bf16_f32 v10, v3, s0
	global_store_short v[6:7], v10, off offset:224
	v_cvt_pk_bf16_f32 v10, v4, s0
	global_store_short v[6:7], v10, off offset:288
	v_cvt_pk_bf16_f32 v10, v5, s0
	global_store_short v[6:7], v10, off offset:352
	v_cvt_pk_bf16_f32 v10, v0, s0
	global_store_short v[6:7], v10, off offset:416
	v_cvt_pk_bf16_f32 v10, v1, s0
	s_mov_b64 s[0:1], 0
	global_store_short v[6:7], v10, off offset:480
